# v19 plus nt hint on the FFN1 HF stores (272 MB per layer, consumed once by FFN2)
# baseline (speedup 1.0000x reference)
.LBB0_1075:
	v_mov_b32_e32 v144, v147
	v_mov_b32_e32 v145, v146
	s_lshl_b32 s54, s90, 8
	s_add_i32 s54, s54, s75
	v_add_u32_e32 v144, s54, v144
	s_lshl_b32 s54, s91, 8
	s_or_b32 s54, s54, s76
	v_lshl_add_u32 v152, v145, 3, s54
	v_ashrrev_i32_e32 v145, 31, v144
	v_max_f32_e32 v120, v120, v120
	v_max_f32_e32 v124, v124, v124
	v_max_f32_e32 v121, v121, v121
	v_max_f32_e32 v125, v125, v125
	v_max_f32_e32 v122, v122, v122
	v_max_f32_e32 v126, v126, v126
	v_max_f32_e32 v123, v123, v123
	v_max_f32_e32 v127, v127, v127
	v_lshlrev_b64 v[144:145], 13, v[144:145]
	v_max_f32_e32 v120, 0, v120
	v_max_f32_e32 v124, 0, v124
	v_max_f32_e32 v121, 0, v121
	v_max_f32_e32 v125, 0, v125
	v_max_f32_e32 v122, 0, v122
	v_max_f32_e32 v126, 0, v126
	v_max_f32_e32 v123, 0, v123
	v_max_f32_e32 v127, 0, v127
	v_ashrrev_i32_e32 v153, 31, v152
	v_lshl_add_u64 v[144:145], s[18:19], 0, v[144:145]
	v_pk_mul_f32 v[120:121], v[120:121], v[120:121]
	v_pk_mul_f32 v[124:125], v[124:125], v[124:125]
	v_pk_mul_f32 v[122:123], v[122:123], v[122:123]
	v_pk_mul_f32 v[126:127], v[126:127], v[126:127]
	v_max_f32_e32 v112, v112, v112
	v_max_f32_e32 v113, v113, v113
	v_lshl_add_u64 v[144:145], v[152:153], 1, v[144:145]
	v_cvt_pk_bf16_f32 v120, v120, v121
	v_cvt_pk_bf16_f32 v121, v122, v123
	v_cvt_pk_bf16_f32 v122, v124, v125
	v_cvt_pk_bf16_f32 v123, v126, v127
	v_max_f32_e32 v112, 0, v112
	v_max_f32_e32 v113, 0, v113
	global_store_dwordx4 v[144:145], v[120:123], off nt
	v_max_f32_e32 v116, v116, v116
	v_max_f32_e32 v117, v117, v117
	v_pk_mul_f32 v[120:121], v[112:113], v[112:113]
	v_max_f32_e32 v113, v114, v114
	v_max_f32_e32 v112, v118, v118
	v_max_f32_e32 v114, 0, v113
	v_max_f32_e32 v113, v119, v119
	v_max_f32_e32 v115, v115, v115
	v_max_f32_e32 v116, 0, v116
	v_max_f32_e32 v117, 0, v117
	v_max_f32_e32 v112, 0, v112
	v_max_f32_e32 v113, 0, v113
	v_max_f32_e32 v115, 0, v115
	v_pk_mul_f32 v[116:117], v[116:117], v[116:117]
	v_pk_mul_f32 v[118:119], v[112:113], v[112:113]
	v_pk_mul_f32 v[122:123], v[114:115], v[114:115]
	v_max_f32_e32 v104, v104, v104
	v_max_f32_e32 v105, v105, v105
	v_cvt_pk_bf16_f32 v112, v116, v117
	v_cvt_pk_bf16_f32 v113, v118, v119
	v_cvt_pk_bf16_f32 v114, v120, v121
	v_cvt_pk_bf16_f32 v115, v122, v123
	v_max_f32_e32 v104, 0, v104
	v_max_f32_e32 v105, 0, v105
	global_store_dwordx4 v[144:145], v[112:115], off offset:256 nt
	v_max_f32_e32 v108, v108, v108
	v_max_f32_e32 v109, v109, v109
	v_pk_mul_f32 v[114:115], v[104:105], v[104:105]
	v_max_f32_e32 v105, v106, v106
	v_max_f32_e32 v108, 0, v108
	v_max_f32_e32 v109, 0, v109
	v_max_f32_e32 v104, v110, v110
	v_max_f32_e32 v106, 0, v105
	v_max_f32_e32 v105, v111, v111
	v_max_f32_e32 v107, v107, v107
	v_pk_mul_f32 v[108:109], v[108:109], v[108:109]
	v_max_f32_e32 v104, 0, v104
	v_max_f32_e32 v105, 0, v105
	v_max_f32_e32 v107, 0, v107
	v_pk_mul_f32 v[110:111], v[104:105], v[104:105]
	v_pk_mul_f32 v[116:117], v[106:107], v[106:107]
	v_cvt_pk_bf16_f32 v104, v108, v109
	v_add_co_u32_e32 v108, vcc, s81, v144
	v_max_f32_e32 v96, v96, v96
	v_max_f32_e32 v97, v97, v97
	v_cvt_pk_bf16_f32 v105, v110, v111
	v_cvt_pk_bf16_f32 v106, v114, v115
	v_cvt_pk_bf16_f32 v107, v116, v117
	v_addc_co_u32_e32 v109, vcc, 0, v145, vcc
	v_max_f32_e32 v96, 0, v96
	v_max_f32_e32 v97, 0, v97
	global_store_dwordx4 v[108:109], v[104:107], off nt
	v_max_f32_e32 v100, v100, v100
	v_max_f32_e32 v101, v101, v101
	v_pk_mul_f32 v[104:105], v[96:97], v[96:97]
	v_max_f32_e32 v97, v98, v98
	v_max_f32_e32 v96, v102, v102
	v_max_f32_e32 v98, 0, v97
	v_max_f32_e32 v97, v103, v103
	v_max_f32_e32 v99, v99, v99
	v_max_f32_e32 v100, 0, v100
	v_max_f32_e32 v101, 0, v101
	v_max_f32_e32 v96, 0, v96
	v_max_f32_e32 v97, 0, v97
	v_max_f32_e32 v99, 0, v99
	v_pk_mul_f32 v[100:101], v[100:101], v[100:101]
	v_pk_mul_f32 v[102:103], v[96:97], v[96:97]
	v_pk_mul_f32 v[106:107], v[98:99], v[98:99]
	v_max_f32_e32 v88, v88, v88
	v_max_f32_e32 v89, v89, v89
	v_lshl_add_u64 v[112:113], v[144:145], 0, s[26:27]
	v_cvt_pk_bf16_f32 v96, v100, v101
	v_cvt_pk_bf16_f32 v97, v102, v103
	v_cvt_pk_bf16_f32 v98, v104, v105
	v_cvt_pk_bf16_f32 v99, v106, v107
	v_max_f32_e32 v88, 0, v88
	v_max_f32_e32 v89, 0, v89
	global_store_dwordx4 v[112:113], v[96:99], off offset:256 nt
	v_max_f32_e32 v92, v92, v92
	v_max_f32_e32 v93, v93, v93
	v_pk_mul_f32 v[98:99], v[88:89], v[88:89]
	v_max_f32_e32 v89, v90, v90
	v_max_f32_e32 v92, 0, v92
	v_max_f32_e32 v93, 0, v93
	v_max_f32_e32 v88, v94, v94
	v_max_f32_e32 v90, 0, v89
	v_max_f32_e32 v89, v95, v95
	v_max_f32_e32 v91, v91, v91
	v_pk_mul_f32 v[92:93], v[92:93], v[92:93]
	v_max_f32_e32 v88, 0, v88
	v_max_f32_e32 v89, 0, v89
	v_max_f32_e32 v91, 0, v91
	v_pk_mul_f32 v[94:95], v[88:89], v[88:89]
	v_pk_mul_f32 v[100:101], v[90:91], v[90:91]
	v_cvt_pk_bf16_f32 v88, v92, v93
	v_add_co_u32_e32 v92, vcc, s82, v144
	v_max_f32_e32 v80, v80, v80
	v_max_f32_e32 v81, v81, v81
	v_cvt_pk_bf16_f32 v89, v94, v95
	v_cvt_pk_bf16_f32 v90, v98, v99
	v_cvt_pk_bf16_f32 v91, v100, v101
	v_addc_co_u32_e32 v93, vcc, 0, v145, vcc
	v_max_f32_e32 v80, 0, v80
	v_max_f32_e32 v81, 0, v81
	global_store_dwordx4 v[92:93], v[88:91], off nt
	v_max_f32_e32 v84, v84, v84
	v_max_f32_e32 v85, v85, v85
	v_pk_mul_f32 v[88:89], v[80:81], v[80:81]
	v_max_f32_e32 v81, v82, v82
	v_max_f32_e32 v80, v86, v86
	v_max_f32_e32 v82, 0, v81
	v_max_f32_e32 v81, v87, v87
	v_max_f32_e32 v83, v83, v83
	v_max_f32_e32 v84, 0, v84
	v_max_f32_e32 v85, 0, v85
	v_max_f32_e32 v80, 0, v80
	v_max_f32_e32 v81, 0, v81
	v_max_f32_e32 v83, 0, v83
	v_pk_mul_f32 v[84:85], v[84:85], v[84:85]
	v_pk_mul_f32 v[86:87], v[80:81], v[80:81]
	v_pk_mul_f32 v[90:91], v[82:83], v[82:83]
	v_max_f32_e32 v72, v72, v72
	v_max_f32_e32 v73, v73, v73
	v_lshl_add_u64 v[96:97], v[144:145], 0, s[28:29]
	v_cvt_pk_bf16_f32 v80, v84, v85
	v_cvt_pk_bf16_f32 v81, v86, v87
	v_cvt_pk_bf16_f32 v82, v88, v89
	v_cvt_pk_bf16_f32 v83, v90, v91
	v_max_f32_e32 v72, 0, v72
	v_max_f32_e32 v73, 0, v73
	global_store_dwordx4 v[96:97], v[80:83], off offset:256 nt
	v_max_f32_e32 v76, v76, v76
	v_max_f32_e32 v77, v77, v77
	v_pk_mul_f32 v[82:83], v[72:73], v[72:73]
	v_max_f32_e32 v73, v74, v74
	v_max_f32_e32 v76, 0, v76
	v_max_f32_e32 v77, 0, v77
	v_max_f32_e32 v72, v78, v78
	v_max_f32_e32 v74, 0, v73
	v_max_f32_e32 v73, v79, v79
	v_max_f32_e32 v75, v75, v75
	v_pk_mul_f32 v[76:77], v[76:77], v[76:77]
	v_max_f32_e32 v72, 0, v72
	v_max_f32_e32 v73, 0, v73
	v_max_f32_e32 v75, 0, v75
	v_pk_mul_f32 v[78:79], v[72:73], v[72:73]
	v_pk_mul_f32 v[84:85], v[74:75], v[74:75]
	v_cvt_pk_bf16_f32 v72, v76, v77
	v_add_co_u32_e32 v76, vcc, s83, v144
	v_max_f32_e32 v64, v64, v64
	v_max_f32_e32 v65, v65, v65
	v_cvt_pk_bf16_f32 v73, v78, v79
	v_cvt_pk_bf16_f32 v74, v82, v83
	v_cvt_pk_bf16_f32 v75, v84, v85
	v_addc_co_u32_e32 v77, vcc, 0, v145, vcc
	v_max_f32_e32 v64, 0, v64
	v_max_f32_e32 v65, 0, v65
	global_store_dwordx4 v[76:77], v[72:75], off nt
	v_max_f32_e32 v68, v68, v68
	v_max_f32_e32 v69, v69, v69
	v_pk_mul_f32 v[72:73], v[64:65], v[64:65]
	v_max_f32_e32 v65, v66, v66
	v_max_f32_e32 v64, v70, v70
	v_max_f32_e32 v66, 0, v65
	v_max_f32_e32 v65, v71, v71
	v_max_f32_e32 v67, v67, v67
	v_max_f32_e32 v68, 0, v68
	v_max_f32_e32 v69, 0, v69
	v_max_f32_e32 v64, 0, v64
	v_max_f32_e32 v65, 0, v65
	v_max_f32_e32 v67, 0, v67
	v_pk_mul_f32 v[68:69], v[68:69], v[68:69]
	v_pk_mul_f32 v[70:71], v[64:65], v[64:65]
	v_pk_mul_f32 v[74:75], v[66:67], v[66:67]
	v_max_f32_e32 v56, v56, v56
	v_max_f32_e32 v57, v57, v57
	v_lshl_add_u64 v[80:81], v[144:145], 0, s[30:31]
	v_cvt_pk_bf16_f32 v64, v68, v69
	v_cvt_pk_bf16_f32 v65, v70, v71
	v_cvt_pk_bf16_f32 v66, v72, v73
	v_cvt_pk_bf16_f32 v67, v74, v75
	v_max_f32_e32 v56, 0, v56
	v_max_f32_e32 v57, 0, v57
	global_store_dwordx4 v[80:81], v[64:67], off offset:256 nt
	v_max_f32_e32 v60, v60, v60
	v_max_f32_e32 v61, v61, v61
	v_pk_mul_f32 v[66:67], v[56:57], v[56:57]
	v_max_f32_e32 v57, v58, v58
	v_max_f32_e32 v60, 0, v60
	v_max_f32_e32 v61, 0, v61
	v_max_f32_e32 v56, v62, v62
	v_max_f32_e32 v58, 0, v57
	v_max_f32_e32 v57, v63, v63
	v_max_f32_e32 v59, v59, v59
	v_pk_mul_f32 v[60:61], v[60:61], v[60:61]
	v_max_f32_e32 v56, 0, v56
	v_max_f32_e32 v57, 0, v57
	v_max_f32_e32 v59, 0, v59
	v_pk_mul_f32 v[62:63], v[56:57], v[56:57]
	v_pk_mul_f32 v[68:69], v[58:59], v[58:59]
	v_cvt_pk_bf16_f32 v56, v60, v61
	v_add_co_u32_e32 v60, vcc, s84, v144
	v_max_f32_e32 v48, v48, v48
	v_max_f32_e32 v49, v49, v49
	v_cvt_pk_bf16_f32 v57, v62, v63
	v_cvt_pk_bf16_f32 v58, v66, v67
	v_cvt_pk_bf16_f32 v59, v68, v69
	v_addc_co_u32_e32 v61, vcc, 0, v145, vcc
	v_max_f32_e32 v48, 0, v48
	v_max_f32_e32 v49, 0, v49
	global_store_dwordx4 v[60:61], v[56:59], off nt
	v_max_f32_e32 v52, v52, v52
	v_max_f32_e32 v53, v53, v53
	v_pk_mul_f32 v[56:57], v[48:49], v[48:49]
	v_max_f32_e32 v49, v50, v50
	v_max_f32_e32 v48, v54, v54
	v_max_f32_e32 v50, 0, v49
	v_max_f32_e32 v49, v55, v55
	v_max_f32_e32 v51, v51, v51
	v_max_f32_e32 v52, 0, v52
	v_max_f32_e32 v53, 0, v53
	v_max_f32_e32 v48, 0, v48
	v_max_f32_e32 v49, 0, v49
	v_max_f32_e32 v51, 0, v51
	v_pk_mul_f32 v[52:53], v[52:53], v[52:53]
	v_pk_mul_f32 v[54:55], v[48:49], v[48:49]
	v_pk_mul_f32 v[58:59], v[50:51], v[50:51]
	v_max_f32_e32 v40, v40, v40
	v_max_f32_e32 v41, v41, v41
	v_lshl_add_u64 v[64:65], v[144:145], 0, s[44:45]
	v_cvt_pk_bf16_f32 v48, v52, v53
	v_cvt_pk_bf16_f32 v49, v54, v55
	v_cvt_pk_bf16_f32 v50, v56, v57
	v_cvt_pk_bf16_f32 v51, v58, v59
	v_max_f32_e32 v40, 0, v40
	v_max_f32_e32 v41, 0, v41
	global_store_dwordx4 v[64:65], v[48:51], off offset:256 nt
	v_max_f32_e32 v44, v44, v44
	v_max_f32_e32 v45, v45, v45
	v_pk_mul_f32 v[50:51], v[40:41], v[40:41]
	v_max_f32_e32 v41, v42, v42
	v_max_f32_e32 v44, 0, v44
	v_max_f32_e32 v45, 0, v45
	v_max_f32_e32 v40, v46, v46
	v_max_f32_e32 v42, 0, v41
	v_max_f32_e32 v41, v47, v47
	v_max_f32_e32 v43, v43, v43
	v_pk_mul_f32 v[44:45], v[44:45], v[44:45]
	v_max_f32_e32 v40, 0, v40
	v_max_f32_e32 v41, 0, v41
	v_max_f32_e32 v43, 0, v43
	v_pk_mul_f32 v[46:47], v[40:41], v[40:41]
	v_pk_mul_f32 v[52:53], v[42:43], v[42:43]
	v_cvt_pk_bf16_f32 v40, v44, v45
	v_add_co_u32_e32 v44, vcc, s85, v144
	v_max_f32_e32 v32, v32, v32
	v_max_f32_e32 v33, v33, v33
	v_cvt_pk_bf16_f32 v41, v46, v47
	v_cvt_pk_bf16_f32 v42, v50, v51
	v_cvt_pk_bf16_f32 v43, v52, v53
	v_addc_co_u32_e32 v45, vcc, 0, v145, vcc
	v_max_f32_e32 v32, 0, v32
	v_max_f32_e32 v33, 0, v33
	global_store_dwordx4 v[44:45], v[40:43], off nt
	v_max_f32_e32 v36, v36, v36
	v_max_f32_e32 v37, v37, v37
	v_pk_mul_f32 v[40:41], v[32:33], v[32:33]
	v_max_f32_e32 v33, v34, v34
	v_max_f32_e32 v32, v38, v38
	v_max_f32_e32 v34, 0, v33
	v_max_f32_e32 v33, v39, v39
	v_max_f32_e32 v35, v35, v35
	v_max_f32_e32 v36, 0, v36
	v_max_f32_e32 v37, 0, v37
	v_max_f32_e32 v32, 0, v32
	v_max_f32_e32 v33, 0, v33
	v_max_f32_e32 v35, 0, v35
	v_pk_mul_f32 v[36:37], v[36:37], v[36:37]
	v_pk_mul_f32 v[38:39], v[32:33], v[32:33]
	v_pk_mul_f32 v[42:43], v[34:35], v[34:35]
	v_max_f32_e32 v24, v24, v24
	v_max_f32_e32 v25, v25, v25
	v_lshl_add_u64 v[48:49], v[144:145], 0, s[46:47]
	v_cvt_pk_bf16_f32 v32, v36, v37
	v_cvt_pk_bf16_f32 v33, v38, v39
	v_cvt_pk_bf16_f32 v34, v40, v41
	v_cvt_pk_bf16_f32 v35, v42, v43
	v_max_f32_e32 v24, 0, v24
	v_max_f32_e32 v25, 0, v25
	global_store_dwordx4 v[48:49], v[32:35], off offset:256 nt
	v_max_f32_e32 v28, v28, v28
	v_max_f32_e32 v29, v29, v29
	v_pk_mul_f32 v[34:35], v[24:25], v[24:25]
	v_max_f32_e32 v25, v26, v26
	v_max_f32_e32 v28, 0, v28
	v_max_f32_e32 v29, 0, v29
	v_max_f32_e32 v24, v30, v30
	v_max_f32_e32 v26, 0, v25
	v_max_f32_e32 v25, v31, v31
	v_max_f32_e32 v27, v27, v27
	v_pk_mul_f32 v[28:29], v[28:29], v[28:29]
	v_max_f32_e32 v24, 0, v24
	v_max_f32_e32 v25, 0, v25
	v_max_f32_e32 v27, 0, v27
	v_pk_mul_f32 v[30:31], v[24:25], v[24:25]
	v_pk_mul_f32 v[36:37], v[26:27], v[26:27]
	v_cvt_pk_bf16_f32 v24, v28, v29
	v_add_co_u32_e32 v28, vcc, s86, v144
	v_max_f32_e32 v16, v16, v16
	v_max_f32_e32 v17, v17, v17
	v_cvt_pk_bf16_f32 v25, v30, v31
	v_cvt_pk_bf16_f32 v26, v34, v35
	v_cvt_pk_bf16_f32 v27, v36, v37
	v_addc_co_u32_e32 v29, vcc, 0, v145, vcc
	v_max_f32_e32 v16, 0, v16
	v_max_f32_e32 v17, 0, v17
	global_store_dwordx4 v[28:29], v[24:27], off nt
	v_max_f32_e32 v20, v20, v20
	v_max_f32_e32 v21, v21, v21
	v_pk_mul_f32 v[24:25], v[16:17], v[16:17]
	v_max_f32_e32 v17, v18, v18
	v_max_f32_e32 v16, v22, v22
	v_max_f32_e32 v18, 0, v17
	v_max_f32_e32 v17, v23, v23
	v_max_f32_e32 v19, v19, v19
	v_max_f32_e32 v20, 0, v20
	v_max_f32_e32 v21, 0, v21
	v_max_f32_e32 v16, 0, v16
	v_max_f32_e32 v17, 0, v17
	v_max_f32_e32 v19, 0, v19
	v_pk_mul_f32 v[20:21], v[20:21], v[20:21]
	v_pk_mul_f32 v[22:23], v[16:17], v[16:17]
	v_pk_mul_f32 v[26:27], v[18:19], v[18:19]
	v_max_f32_e32 v8, v8, v8
	v_max_f32_e32 v9, v9, v9
	v_lshl_add_u64 v[32:33], v[144:145], 0, s[48:49]
	v_cvt_pk_bf16_f32 v16, v20, v21
	v_cvt_pk_bf16_f32 v17, v22, v23
	v_cvt_pk_bf16_f32 v18, v24, v25
	v_cvt_pk_bf16_f32 v19, v26, v27
	v_max_f32_e32 v8, 0, v8
	v_max_f32_e32 v9, 0, v9
	global_store_dwordx4 v[32:33], v[16:19], off offset:256 nt
	v_max_f32_e32 v12, v12, v12
	v_max_f32_e32 v13, v13, v13
	v_pk_mul_f32 v[18:19], v[8:9], v[8:9]
	v_max_f32_e32 v9, v10, v10
	v_max_f32_e32 v12, 0, v12
	v_max_f32_e32 v13, 0, v13
	v_max_f32_e32 v8, v14, v14
	v_max_f32_e32 v10, 0, v9
	v_max_f32_e32 v9, v15, v15
	v_max_f32_e32 v11, v11, v11
	v_pk_mul_f32 v[12:13], v[12:13], v[12:13]
	v_max_f32_e32 v8, 0, v8
	v_max_f32_e32 v9, 0, v9
	v_max_f32_e32 v11, 0, v11
	v_pk_mul_f32 v[14:15], v[8:9], v[8:9]
	v_pk_mul_f32 v[20:21], v[10:11], v[10:11]
	v_cvt_pk_bf16_f32 v8, v12, v13
	v_add_co_u32_e32 v12, vcc, s87, v144
	v_max_f32_e32 v0, v0, v0
	v_max_f32_e32 v1, v1, v1
	v_cvt_pk_bf16_f32 v9, v14, v15
	v_cvt_pk_bf16_f32 v10, v18, v19
	v_cvt_pk_bf16_f32 v11, v20, v21
	v_addc_co_u32_e32 v13, vcc, 0, v145, vcc
	v_max_f32_e32 v0, 0, v0
	v_max_f32_e32 v1, 0, v1
	global_store_dwordx4 v[12:13], v[8:11], off nt
	v_max_f32_e32 v4, v4, v4
	v_max_f32_e32 v5, v5, v5
	v_pk_mul_f32 v[8:9], v[0:1], v[0:1]
	v_max_f32_e32 v1, v2, v2
	v_max_f32_e32 v0, v6, v6
	v_max_f32_e32 v2, 0, v1
	v_max_f32_e32 v1, v7, v7
	v_max_f32_e32 v3, v3, v3
	v_max_f32_e32 v4, 0, v4
	v_max_f32_e32 v5, 0, v5
	v_max_f32_e32 v0, 0, v0
	v_max_f32_e32 v1, 0, v1
	v_max_f32_e32 v3, 0, v3
	v_pk_mul_f32 v[4:5], v[4:5], v[4:5]
	v_pk_mul_f32 v[6:7], v[0:1], v[0:1]
	v_pk_mul_f32 v[10:11], v[2:3], v[2:3]
	v_lshl_add_u64 v[16:17], v[144:145], 0, s[50:51]
	v_cvt_pk_bf16_f32 v0, v4, v5
	v_cvt_pk_bf16_f32 v1, v6, v7
	v_cvt_pk_bf16_f32 v2, v8, v9
	v_cvt_pk_bf16_f32 v3, v10, v11
	s_and_b64 vcc, exec, s[6:7]
	s_mov_b64 s[6:7], -1
	global_store_dwordx4 v[16:17], v[0:3], off offset:256 nt
	s_cbranch_vccnz .LBB0_1063
	s_andn2_b64 vcc, exec, s[16:17]
	s_cbranch_vccnz .LBB0_1062
	s_barrier
	s_branch .LBB0_1062

.LBB0_1767:
	v_mov_b32_e32 v144, v147
	v_mov_b32_e32 v145, v146
	s_lshl_b32 s52, s88, 8
	s_add_i32 s52, s52, s73
	v_add_u32_e32 v144, s52, v144
	s_lshl_b32 s52, s89, 8
	s_or_b32 s52, s52, s74
	v_lshl_add_u32 v152, v145, 3, s52
	v_ashrrev_i32_e32 v145, 31, v144
	v_max_f32_e32 v120, v120, v120
	v_max_f32_e32 v124, v124, v124
	v_max_f32_e32 v121, v121, v121
	v_max_f32_e32 v125, v125, v125
	v_max_f32_e32 v122, v122, v122
	v_max_f32_e32 v126, v126, v126
	v_max_f32_e32 v123, v123, v123
	v_max_f32_e32 v127, v127, v127
	v_lshlrev_b64 v[144:145], 13, v[144:145]
	v_max_f32_e32 v120, 0, v120
	v_max_f32_e32 v124, 0, v124
	v_max_f32_e32 v121, 0, v121
	v_max_f32_e32 v125, 0, v125
	v_max_f32_e32 v122, 0, v122
	v_max_f32_e32 v126, 0, v126
	v_max_f32_e32 v123, 0, v123
	v_max_f32_e32 v127, 0, v127
	v_ashrrev_i32_e32 v153, 31, v152
	v_lshl_add_u64 v[144:145], s[16:17], 0, v[144:145]
	v_pk_mul_f32 v[120:121], v[120:121], v[120:121]
	v_pk_mul_f32 v[124:125], v[124:125], v[124:125]
	v_pk_mul_f32 v[122:123], v[122:123], v[122:123]
	v_pk_mul_f32 v[126:127], v[126:127], v[126:127]
	v_max_f32_e32 v112, v112, v112
	v_max_f32_e32 v113, v113, v113
	v_lshl_add_u64 v[144:145], v[152:153], 1, v[144:145]
	v_cvt_pk_bf16_f32 v120, v120, v121
	v_cvt_pk_bf16_f32 v121, v122, v123
	v_cvt_pk_bf16_f32 v122, v124, v125
	v_cvt_pk_bf16_f32 v123, v126, v127
	v_max_f32_e32 v112, 0, v112
	v_max_f32_e32 v113, 0, v113
	global_store_dwordx4 v[144:145], v[120:123], off nt
	v_max_f32_e32 v116, v116, v116
	v_max_f32_e32 v117, v117, v117
	v_pk_mul_f32 v[120:121], v[112:113], v[112:113]
	v_max_f32_e32 v113, v114, v114
	v_max_f32_e32 v112, v118, v118
	v_max_f32_e32 v114, 0, v113
	v_max_f32_e32 v113, v119, v119
	v_max_f32_e32 v115, v115, v115
	v_max_f32_e32 v116, 0, v116
	v_max_f32_e32 v117, 0, v117
	v_max_f32_e32 v112, 0, v112
	v_max_f32_e32 v113, 0, v113
	v_max_f32_e32 v115, 0, v115
	v_pk_mul_f32 v[116:117], v[116:117], v[116:117]
	v_pk_mul_f32 v[118:119], v[112:113], v[112:113]
	v_pk_mul_f32 v[122:123], v[114:115], v[114:115]
	v_max_f32_e32 v104, v104, v104
	v_max_f32_e32 v105, v105, v105
	v_cvt_pk_bf16_f32 v112, v116, v117
	v_cvt_pk_bf16_f32 v113, v118, v119
	v_cvt_pk_bf16_f32 v114, v120, v121
	v_cvt_pk_bf16_f32 v115, v122, v123
	v_max_f32_e32 v104, 0, v104
	v_max_f32_e32 v105, 0, v105
	global_store_dwordx4 v[144:145], v[112:115], off offset:256 nt
	v_max_f32_e32 v108, v108, v108
	v_max_f32_e32 v109, v109, v109
	v_pk_mul_f32 v[114:115], v[104:105], v[104:105]
	v_max_f32_e32 v105, v106, v106
	v_max_f32_e32 v108, 0, v108
	v_max_f32_e32 v109, 0, v109
	v_max_f32_e32 v104, v110, v110
	v_max_f32_e32 v106, 0, v105
	v_max_f32_e32 v105, v111, v111
	v_max_f32_e32 v107, v107, v107
	v_pk_mul_f32 v[108:109], v[108:109], v[108:109]
	v_max_f32_e32 v104, 0, v104
	v_max_f32_e32 v105, 0, v105
	v_max_f32_e32 v107, 0, v107
	v_pk_mul_f32 v[110:111], v[104:105], v[104:105]
	v_pk_mul_f32 v[116:117], v[106:107], v[106:107]
	v_cvt_pk_bf16_f32 v104, v108, v109
	v_add_co_u32_e32 v108, vcc, s79, v144
	v_max_f32_e32 v96, v96, v96
	v_max_f32_e32 v97, v97, v97
	v_cvt_pk_bf16_f32 v105, v110, v111
	v_cvt_pk_bf16_f32 v106, v114, v115
	v_cvt_pk_bf16_f32 v107, v116, v117
	v_addc_co_u32_e32 v109, vcc, 0, v145, vcc
	v_max_f32_e32 v96, 0, v96
	v_max_f32_e32 v97, 0, v97
	global_store_dwordx4 v[108:109], v[104:107], off nt
	v_max_f32_e32 v100, v100, v100
	v_max_f32_e32 v101, v101, v101
	v_pk_mul_f32 v[104:105], v[96:97], v[96:97]
	v_max_f32_e32 v97, v98, v98
	v_max_f32_e32 v96, v102, v102
	v_max_f32_e32 v98, 0, v97
	v_max_f32_e32 v97, v103, v103
	v_max_f32_e32 v99, v99, v99
	v_max_f32_e32 v100, 0, v100
	v_max_f32_e32 v101, 0, v101
	v_max_f32_e32 v96, 0, v96
	v_max_f32_e32 v97, 0, v97
	v_max_f32_e32 v99, 0, v99
	v_pk_mul_f32 v[100:101], v[100:101], v[100:101]
	v_pk_mul_f32 v[102:103], v[96:97], v[96:97]
	v_pk_mul_f32 v[106:107], v[98:99], v[98:99]
	v_max_f32_e32 v88, v88, v88
	v_max_f32_e32 v89, v89, v89
	v_lshl_add_u64 v[112:113], v[144:145], 0, s[24:25]
	v_cvt_pk_bf16_f32 v96, v100, v101
	v_cvt_pk_bf16_f32 v97, v102, v103
	v_cvt_pk_bf16_f32 v98, v104, v105
	v_cvt_pk_bf16_f32 v99, v106, v107
	v_max_f32_e32 v88, 0, v88
	v_max_f32_e32 v89, 0, v89
	global_store_dwordx4 v[112:113], v[96:99], off offset:256 nt
	v_max_f32_e32 v92, v92, v92
	v_max_f32_e32 v93, v93, v93
	v_pk_mul_f32 v[98:99], v[88:89], v[88:89]
	v_max_f32_e32 v89, v90, v90
	v_max_f32_e32 v92, 0, v92
	v_max_f32_e32 v93, 0, v93
	v_max_f32_e32 v88, v94, v94
	v_max_f32_e32 v90, 0, v89
	v_max_f32_e32 v89, v95, v95
	v_max_f32_e32 v91, v91, v91
	v_pk_mul_f32 v[92:93], v[92:93], v[92:93]
	v_max_f32_e32 v88, 0, v88
	v_max_f32_e32 v89, 0, v89
	v_max_f32_e32 v91, 0, v91
	v_pk_mul_f32 v[94:95], v[88:89], v[88:89]
	v_pk_mul_f32 v[100:101], v[90:91], v[90:91]
	v_cvt_pk_bf16_f32 v88, v92, v93
	v_add_co_u32_e32 v92, vcc, s80, v144
	v_max_f32_e32 v80, v80, v80
	v_max_f32_e32 v81, v81, v81
	v_cvt_pk_bf16_f32 v89, v94, v95
	v_cvt_pk_bf16_f32 v90, v98, v99
	v_cvt_pk_bf16_f32 v91, v100, v101
	v_addc_co_u32_e32 v93, vcc, 0, v145, vcc
	v_max_f32_e32 v80, 0, v80
	v_max_f32_e32 v81, 0, v81
	global_store_dwordx4 v[92:93], v[88:91], off nt
	v_max_f32_e32 v84, v84, v84
	v_max_f32_e32 v85, v85, v85
	v_pk_mul_f32 v[88:89], v[80:81], v[80:81]
	v_max_f32_e32 v81, v82, v82
	v_max_f32_e32 v80, v86, v86
	v_max_f32_e32 v82, 0, v81
	v_max_f32_e32 v81, v87, v87
	v_max_f32_e32 v83, v83, v83
	v_max_f32_e32 v84, 0, v84
	v_max_f32_e32 v85, 0, v85
	v_max_f32_e32 v80, 0, v80
	v_max_f32_e32 v81, 0, v81
	v_max_f32_e32 v83, 0, v83
	v_pk_mul_f32 v[84:85], v[84:85], v[84:85]
	v_pk_mul_f32 v[86:87], v[80:81], v[80:81]
	v_pk_mul_f32 v[90:91], v[82:83], v[82:83]
	v_max_f32_e32 v72, v72, v72
	v_max_f32_e32 v73, v73, v73
	v_lshl_add_u64 v[96:97], v[144:145], 0, s[26:27]
	v_cvt_pk_bf16_f32 v80, v84, v85
	v_cvt_pk_bf16_f32 v81, v86, v87
	v_cvt_pk_bf16_f32 v82, v88, v89
	v_cvt_pk_bf16_f32 v83, v90, v91
	v_max_f32_e32 v72, 0, v72
	v_max_f32_e32 v73, 0, v73
	global_store_dwordx4 v[96:97], v[80:83], off offset:256 nt
	v_max_f32_e32 v76, v76, v76
	v_max_f32_e32 v77, v77, v77
	v_pk_mul_f32 v[82:83], v[72:73], v[72:73]
	v_max_f32_e32 v73, v74, v74
	v_max_f32_e32 v76, 0, v76
	v_max_f32_e32 v77, 0, v77
	v_max_f32_e32 v72, v78, v78
	v_max_f32_e32 v74, 0, v73
	v_max_f32_e32 v73, v79, v79
	v_max_f32_e32 v75, v75, v75
	v_pk_mul_f32 v[76:77], v[76:77], v[76:77]
	v_max_f32_e32 v72, 0, v72
	v_max_f32_e32 v73, 0, v73
	v_max_f32_e32 v75, 0, v75
	v_pk_mul_f32 v[78:79], v[72:73], v[72:73]
	v_pk_mul_f32 v[84:85], v[74:75], v[74:75]
	v_cvt_pk_bf16_f32 v72, v76, v77
	v_add_co_u32_e32 v76, vcc, s81, v144
	v_max_f32_e32 v64, v64, v64
	v_max_f32_e32 v65, v65, v65
	v_cvt_pk_bf16_f32 v73, v78, v79
	v_cvt_pk_bf16_f32 v74, v82, v83
	v_cvt_pk_bf16_f32 v75, v84, v85
	v_addc_co_u32_e32 v77, vcc, 0, v145, vcc
	v_max_f32_e32 v64, 0, v64
	v_max_f32_e32 v65, 0, v65
	global_store_dwordx4 v[76:77], v[72:75], off nt
	v_max_f32_e32 v68, v68, v68
	v_max_f32_e32 v69, v69, v69
	v_pk_mul_f32 v[72:73], v[64:65], v[64:65]
	v_max_f32_e32 v65, v66, v66
	v_max_f32_e32 v64, v70, v70
	v_max_f32_e32 v66, 0, v65
	v_max_f32_e32 v65, v71, v71
	v_max_f32_e32 v67, v67, v67
	v_max_f32_e32 v68, 0, v68
	v_max_f32_e32 v69, 0, v69
	v_max_f32_e32 v64, 0, v64
	v_max_f32_e32 v65, 0, v65
	v_max_f32_e32 v67, 0, v67
	v_pk_mul_f32 v[68:69], v[68:69], v[68:69]
	v_pk_mul_f32 v[70:71], v[64:65], v[64:65]
	v_pk_mul_f32 v[74:75], v[66:67], v[66:67]
	v_max_f32_e32 v56, v56, v56
	v_max_f32_e32 v57, v57, v57
	v_lshl_add_u64 v[80:81], v[144:145], 0, s[28:29]
	v_cvt_pk_bf16_f32 v64, v68, v69
	v_cvt_pk_bf16_f32 v65, v70, v71
	v_cvt_pk_bf16_f32 v66, v72, v73
	v_cvt_pk_bf16_f32 v67, v74, v75
	v_max_f32_e32 v56, 0, v56
	v_max_f32_e32 v57, 0, v57
	global_store_dwordx4 v[80:81], v[64:67], off offset:256 nt
	v_max_f32_e32 v60, v60, v60
	v_max_f32_e32 v61, v61, v61
	v_pk_mul_f32 v[66:67], v[56:57], v[56:57]
	v_max_f32_e32 v57, v58, v58
	v_max_f32_e32 v60, 0, v60
	v_max_f32_e32 v61, 0, v61
	v_max_f32_e32 v56, v62, v62
	v_max_f32_e32 v58, 0, v57
	v_max_f32_e32 v57, v63, v63
	v_max_f32_e32 v59, v59, v59
	v_pk_mul_f32 v[60:61], v[60:61], v[60:61]
	v_max_f32_e32 v56, 0, v56
	v_max_f32_e32 v57, 0, v57
	v_max_f32_e32 v59, 0, v59
	v_pk_mul_f32 v[62:63], v[56:57], v[56:57]
	v_pk_mul_f32 v[68:69], v[58:59], v[58:59]
	v_cvt_pk_bf16_f32 v56, v60, v61
	v_add_co_u32_e32 v60, vcc, s82, v144
	v_max_f32_e32 v48, v48, v48
	v_max_f32_e32 v49, v49, v49
	v_cvt_pk_bf16_f32 v57, v62, v63
	v_cvt_pk_bf16_f32 v58, v66, v67
	v_cvt_pk_bf16_f32 v59, v68, v69
	v_addc_co_u32_e32 v61, vcc, 0, v145, vcc
	v_max_f32_e32 v48, 0, v48
	v_max_f32_e32 v49, 0, v49
	global_store_dwordx4 v[60:61], v[56:59], off nt
	v_max_f32_e32 v52, v52, v52
	v_max_f32_e32 v53, v53, v53
	v_pk_mul_f32 v[56:57], v[48:49], v[48:49]
	v_max_f32_e32 v49, v50, v50
	v_max_f32_e32 v48, v54, v54
	v_max_f32_e32 v50, 0, v49
	v_max_f32_e32 v49, v55, v55
	v_max_f32_e32 v51, v51, v51
	v_max_f32_e32 v52, 0, v52
	v_max_f32_e32 v53, 0, v53
	v_max_f32_e32 v48, 0, v48
	v_max_f32_e32 v49, 0, v49
	v_max_f32_e32 v51, 0, v51
	v_pk_mul_f32 v[52:53], v[52:53], v[52:53]
	v_pk_mul_f32 v[54:55], v[48:49], v[48:49]
	v_pk_mul_f32 v[58:59], v[50:51], v[50:51]
	v_max_f32_e32 v40, v40, v40
	v_max_f32_e32 v41, v41, v41
	v_lshl_add_u64 v[64:65], v[144:145], 0, s[30:31]
	v_cvt_pk_bf16_f32 v48, v52, v53
	v_cvt_pk_bf16_f32 v49, v54, v55
	v_cvt_pk_bf16_f32 v50, v56, v57
	v_cvt_pk_bf16_f32 v51, v58, v59
	v_max_f32_e32 v40, 0, v40
	v_max_f32_e32 v41, 0, v41
	global_store_dwordx4 v[64:65], v[48:51], off offset:256 nt
	v_max_f32_e32 v44, v44, v44
	v_max_f32_e32 v45, v45, v45
	v_pk_mul_f32 v[50:51], v[40:41], v[40:41]
	v_max_f32_e32 v41, v42, v42
	v_max_f32_e32 v44, 0, v44
	v_max_f32_e32 v45, 0, v45
	v_max_f32_e32 v40, v46, v46
	v_max_f32_e32 v42, 0, v41
	v_max_f32_e32 v41, v47, v47
	v_max_f32_e32 v43, v43, v43
	v_pk_mul_f32 v[44:45], v[44:45], v[44:45]
	v_max_f32_e32 v40, 0, v40
	v_max_f32_e32 v41, 0, v41
	v_max_f32_e32 v43, 0, v43
	v_pk_mul_f32 v[46:47], v[40:41], v[40:41]
	v_pk_mul_f32 v[52:53], v[42:43], v[42:43]
	v_cvt_pk_bf16_f32 v40, v44, v45
	v_add_co_u32_e32 v44, vcc, s83, v144
	v_max_f32_e32 v32, v32, v32
	v_max_f32_e32 v33, v33, v33
	v_cvt_pk_bf16_f32 v41, v46, v47
	v_cvt_pk_bf16_f32 v42, v50, v51
	v_cvt_pk_bf16_f32 v43, v52, v53
	v_addc_co_u32_e32 v45, vcc, 0, v145, vcc
	v_max_f32_e32 v32, 0, v32
	v_max_f32_e32 v33, 0, v33
	global_store_dwordx4 v[44:45], v[40:43], off nt
	v_max_f32_e32 v36, v36, v36
	v_max_f32_e32 v37, v37, v37
	v_pk_mul_f32 v[40:41], v[32:33], v[32:33]
	v_max_f32_e32 v33, v34, v34
	v_max_f32_e32 v32, v38, v38
	v_max_f32_e32 v34, 0, v33
	v_max_f32_e32 v33, v39, v39
	v_max_f32_e32 v35, v35, v35
	v_max_f32_e32 v36, 0, v36
	v_max_f32_e32 v37, 0, v37
	v_max_f32_e32 v32, 0, v32
	v_max_f32_e32 v33, 0, v33
	v_max_f32_e32 v35, 0, v35
	v_pk_mul_f32 v[36:37], v[36:37], v[36:37]
	v_pk_mul_f32 v[38:39], v[32:33], v[32:33]
	v_pk_mul_f32 v[42:43], v[34:35], v[34:35]
	v_max_f32_e32 v24, v24, v24
	v_max_f32_e32 v25, v25, v25
	v_lshl_add_u64 v[48:49], v[144:145], 0, s[44:45]
	v_cvt_pk_bf16_f32 v32, v36, v37
	v_cvt_pk_bf16_f32 v33, v38, v39
	v_cvt_pk_bf16_f32 v34, v40, v41
	v_cvt_pk_bf16_f32 v35, v42, v43
	v_max_f32_e32 v24, 0, v24
	v_max_f32_e32 v25, 0, v25
	global_store_dwordx4 v[48:49], v[32:35], off offset:256 nt
	v_max_f32_e32 v28, v28, v28
	v_max_f32_e32 v29, v29, v29
	v_pk_mul_f32 v[34:35], v[24:25], v[24:25]
	v_max_f32_e32 v25, v26, v26
	v_max_f32_e32 v28, 0, v28
	v_max_f32_e32 v29, 0, v29
	v_max_f32_e32 v24, v30, v30
	v_max_f32_e32 v26, 0, v25
	v_max_f32_e32 v25, v31, v31
	v_max_f32_e32 v27, v27, v27
	v_pk_mul_f32 v[28:29], v[28:29], v[28:29]
	v_max_f32_e32 v24, 0, v24
	v_max_f32_e32 v25, 0, v25
	v_max_f32_e32 v27, 0, v27
	v_pk_mul_f32 v[30:31], v[24:25], v[24:25]
	v_pk_mul_f32 v[36:37], v[26:27], v[26:27]
	v_cvt_pk_bf16_f32 v24, v28, v29
	v_add_co_u32_e32 v28, vcc, s84, v144
	v_max_f32_e32 v16, v16, v16
	v_max_f32_e32 v17, v17, v17
	v_cvt_pk_bf16_f32 v25, v30, v31
	v_cvt_pk_bf16_f32 v26, v34, v35
	v_cvt_pk_bf16_f32 v27, v36, v37
	v_addc_co_u32_e32 v29, vcc, 0, v145, vcc
	v_max_f32_e32 v16, 0, v16
	v_max_f32_e32 v17, 0, v17
	global_store_dwordx4 v[28:29], v[24:27], off nt
	v_max_f32_e32 v20, v20, v20
	v_max_f32_e32 v21, v21, v21
	v_pk_mul_f32 v[24:25], v[16:17], v[16:17]
	v_max_f32_e32 v17, v18, v18
	v_max_f32_e32 v16, v22, v22
	v_max_f32_e32 v18, 0, v17
	v_max_f32_e32 v17, v23, v23
	v_max_f32_e32 v19, v19, v19
	v_max_f32_e32 v20, 0, v20
	v_max_f32_e32 v21, 0, v21
	v_max_f32_e32 v16, 0, v16
	v_max_f32_e32 v17, 0, v17
	v_max_f32_e32 v19, 0, v19
	v_pk_mul_f32 v[20:21], v[20:21], v[20:21]
	v_pk_mul_f32 v[22:23], v[16:17], v[16:17]
	v_pk_mul_f32 v[26:27], v[18:19], v[18:19]
	v_max_f32_e32 v8, v8, v8
	v_max_f32_e32 v9, v9, v9
	v_lshl_add_u64 v[32:33], v[144:145], 0, s[46:47]
	v_cvt_pk_bf16_f32 v16, v20, v21
	v_cvt_pk_bf16_f32 v17, v22, v23
	v_cvt_pk_bf16_f32 v18, v24, v25
	v_cvt_pk_bf16_f32 v19, v26, v27
	v_max_f32_e32 v8, 0, v8
	v_max_f32_e32 v9, 0, v9
	global_store_dwordx4 v[32:33], v[16:19], off offset:256 nt
	v_max_f32_e32 v12, v12, v12
	v_max_f32_e32 v13, v13, v13
	v_pk_mul_f32 v[18:19], v[8:9], v[8:9]
	v_max_f32_e32 v9, v10, v10
	v_max_f32_e32 v12, 0, v12
	v_max_f32_e32 v13, 0, v13
	v_max_f32_e32 v8, v14, v14
	v_max_f32_e32 v10, 0, v9
	v_max_f32_e32 v9, v15, v15
	v_max_f32_e32 v11, v11, v11
	v_pk_mul_f32 v[12:13], v[12:13], v[12:13]
	v_max_f32_e32 v8, 0, v8
	v_max_f32_e32 v9, 0, v9
	v_max_f32_e32 v11, 0, v11
	v_pk_mul_f32 v[14:15], v[8:9], v[8:9]
	v_pk_mul_f32 v[20:21], v[10:11], v[10:11]
	v_cvt_pk_bf16_f32 v8, v12, v13
	v_add_co_u32_e32 v12, vcc, s85, v144
	v_max_f32_e32 v0, v0, v0
	v_max_f32_e32 v1, v1, v1
	v_cvt_pk_bf16_f32 v9, v14, v15
	v_cvt_pk_bf16_f32 v10, v18, v19
	v_cvt_pk_bf16_f32 v11, v20, v21
	v_addc_co_u32_e32 v13, vcc, 0, v145, vcc
	v_max_f32_e32 v0, 0, v0
	v_max_f32_e32 v1, 0, v1
	global_store_dwordx4 v[12:13], v[8:11], off nt
	v_max_f32_e32 v4, v4, v4
	v_max_f32_e32 v5, v5, v5
	v_pk_mul_f32 v[8:9], v[0:1], v[0:1]
	v_max_f32_e32 v1, v2, v2
	v_max_f32_e32 v0, v6, v6
	v_max_f32_e32 v2, 0, v1
	v_max_f32_e32 v1, v7, v7
	v_max_f32_e32 v3, v3, v3
	v_max_f32_e32 v4, 0, v4
	v_max_f32_e32 v5, 0, v5
	v_max_f32_e32 v0, 0, v0
	v_max_f32_e32 v1, 0, v1
	v_max_f32_e32 v3, 0, v3
	v_pk_mul_f32 v[4:5], v[4:5], v[4:5]
	v_pk_mul_f32 v[6:7], v[0:1], v[0:1]
	v_pk_mul_f32 v[10:11], v[2:3], v[2:3]
	v_lshl_add_u64 v[16:17], v[144:145], 0, s[48:49]
	v_cvt_pk_bf16_f32 v0, v4, v5
	v_cvt_pk_bf16_f32 v1, v6, v7
	v_cvt_pk_bf16_f32 v2, v8, v9
	v_cvt_pk_bf16_f32 v3, v10, v11
	s_and_b64 vcc, exec, s[0:1]
	s_mov_b64 s[0:1], -1
	global_store_dwordx4 v[16:17], v[0:3], off offset:256 nt
	s_cbranch_vccnz .LBB0_1755
	s_andn2_b64 vcc, exec, s[14:15]
	s_cbranch_vccnz .LBB0_1754
	s_barrier
	s_branch .LBB0_1754
